# remove compiler-inserted vmcnt(0) from in-proj GEMM K-loop (pipeline drain per iteration)
# speedup vs baseline: 1.0039x; 1.0039x over previous
.LBB0_274:
	ds_read_b128 v[128:131], v211
	ds_read_b128 v[132:135], v211 offset:1024
	ds_read_b128 v[136:139], v211 offset:2048
	ds_read_b128 v[140:143], v211 offset:3072
	s_add_u32 s4, s2, 0xfffc0080
	s_addc_u32 s5, s3, -1
	s_cmp_eq_u32 s69, 12
	s_cselect_b32 s7, s11, s5
	s_cselect_b32 s6, s15, s4
	s_cselect_b32 s5, s36, s39
	s_cselect_b32 s4, s37, s38
	v_lshl_add_u64 v[200:201], s[2:3], 0, v[162:163]
	s_add_i32 m0, s44, 0xc000
	ds_read_b128 v[168:171], v212
	ds_read_b128 v[172:175], v212 offset:1024
	ds_read_b128 v[176:179], v212 offset:2048
	ds_read_b128 v[180:183], v212 offset:3072
	ds_read_b128 v[184:187], v212 offset:4096
	ds_read_b128 v[188:191], v212 offset:5120
	ds_read_b128 v[192:195], v212 offset:6144
	ds_read_b128 v[196:199], v212 offset:7168
	global_load_lds_dwordx4 v[200:201], off
	v_lshl_add_u64 v[200:201], s[2:3], 0, v[164:165]
	s_add_i32 m0, s44, 0xe000
	s_nop 0
	global_load_lds_dwordx4 v[200:201], off
	s_waitcnt lgkmcnt(8)
	s_barrier
	s_waitcnt lgkmcnt(0)
	s_setprio 1
	s_waitcnt lgkmcnt(0)
	v_mfma_f32_16x16x32_bf16 v[124:127], v[128:131], v[168:171], v[124:127]
	v_mfma_f32_16x16x32_bf16 v[120:123], v[136:139], v[168:171], v[120:123]
	v_mfma_f32_16x16x32_bf16 v[108:111], v[128:131], v[176:179], v[108:111]
	v_mfma_f32_16x16x32_bf16 v[104:107], v[136:139], v[176:179], v[104:107]
	v_mfma_f32_16x16x32_bf16 v[92:95], v[128:131], v[184:187], v[92:95]
	v_mfma_f32_16x16x32_bf16 v[88:91], v[136:139], v[184:187], v[88:91]
	v_mfma_f32_16x16x32_bf16 v[76:79], v[128:131], v[192:195], v[76:79]
	v_mfma_f32_16x16x32_bf16 v[72:75], v[136:139], v[192:195], v[72:75]
	v_mfma_f32_16x16x32_bf16 v[124:127], v[132:135], v[172:175], v[124:127]
	v_mfma_f32_16x16x32_bf16 v[120:123], v[140:143], v[172:175], v[120:123]
	v_mfma_f32_16x16x32_bf16 v[108:111], v[132:135], v[180:183], v[108:111]
	v_mfma_f32_16x16x32_bf16 v[104:107], v[140:143], v[180:183], v[104:107]
	v_mfma_f32_16x16x32_bf16 v[92:95], v[132:135], v[188:191], v[92:95]
	v_mfma_f32_16x16x32_bf16 v[88:91], v[140:143], v[188:191], v[88:91]
	v_mfma_f32_16x16x32_bf16 v[76:79], v[132:135], v[196:199], v[76:79]
	v_mfma_f32_16x16x32_bf16 v[72:75], v[140:143], v[196:199], v[72:75]
	s_setprio 0
	s_barrier
	s_mov_b32 m0, s42
	v_lshl_add_u64 v[200:201], s[4:5], 0, v[144:145]
	ds_read_b128 v[222:225], v213
	ds_read_b128 v[226:229], v213 offset:1024
	ds_read_b128 v[230:233], v213 offset:2048
	ds_read_b128 v[234:237], v213 offset:3072
	global_load_lds_dwordx4 v[200:201], off
	v_lshl_add_u64 v[238:239], s[4:5], 0, v[146:147]
	s_mov_b32 m0, s43
	s_nop 0
	global_load_lds_dwordx4 v[238:239], off
	s_barrier
	s_waitcnt lgkmcnt(0)
	s_setprio 1
	s_waitcnt lgkmcnt(0)
	v_mfma_f32_16x16x32_bf16 v[116:119], v[222:225], v[168:171], v[116:119]
	v_mfma_f32_16x16x32_bf16 v[112:115], v[230:233], v[168:171], v[112:115]
	v_mfma_f32_16x16x32_bf16 v[100:103], v[222:225], v[176:179], v[100:103]
	v_mfma_f32_16x16x32_bf16 v[96:99], v[230:233], v[176:179], v[96:99]
	v_mfma_f32_16x16x32_bf16 v[84:87], v[222:225], v[184:187], v[84:87]
	v_mfma_f32_16x16x32_bf16 v[80:83], v[230:233], v[184:187], v[80:83]
	v_mfma_f32_16x16x32_bf16 v[68:71], v[222:225], v[192:195], v[68:71]
	v_mfma_f32_16x16x32_bf16 v[64:67], v[230:233], v[192:195], v[64:67]
	v_mfma_f32_16x16x32_bf16 v[116:119], v[226:229], v[172:175], v[116:119]
	v_mfma_f32_16x16x32_bf16 v[112:115], v[234:237], v[172:175], v[112:115]
	v_mfma_f32_16x16x32_bf16 v[100:103], v[226:229], v[180:183], v[100:103]
	v_mfma_f32_16x16x32_bf16 v[96:99], v[234:237], v[180:183], v[96:99]
	v_mfma_f32_16x16x32_bf16 v[84:87], v[226:229], v[188:191], v[84:87]
	v_mfma_f32_16x16x32_bf16 v[80:83], v[234:237], v[188:191], v[80:83]
	v_mfma_f32_16x16x32_bf16 v[68:71], v[226:229], v[196:199], v[68:71]
	v_mfma_f32_16x16x32_bf16 v[64:67], v[234:237], v[196:199], v[64:67]
	s_setprio 0
	s_mov_b32 m0, s44
	v_lshl_add_u64 v[240:241], s[6:7], 0, v[144:145]
	s_barrier
	ds_read_b128 v[168:171], v212 offset:16384
	ds_read_b128 v[172:175], v212 offset:17408
	ds_read_b128 v[176:179], v212 offset:18432
	ds_read_b128 v[180:183], v212 offset:19456
	ds_read_b128 v[184:187], v212 offset:20480
	ds_read_b128 v[188:191], v212 offset:21504
	ds_read_b128 v[192:195], v212 offset:22528
	ds_read_b128 v[196:199], v212 offset:23552
	global_load_lds_dwordx4 v[240:241], off
	v_lshl_add_u64 v[242:243], s[6:7], 0, v[146:147]
	s_mov_b32 m0, s45
	s_nop 0
	global_load_lds_dwordx4 v[242:243], off
	s_barrier
	s_waitcnt lgkmcnt(0)
	s_setprio 1
	s_waitcnt lgkmcnt(0)
	v_mfma_f32_16x16x32_bf16 v[60:63], v[128:131], v[168:171], v[60:63]
	v_mfma_f32_16x16x32_bf16 v[56:59], v[136:139], v[168:171], v[56:59]
	v_mfma_f32_16x16x32_bf16 v[44:47], v[128:131], v[176:179], v[44:47]
	v_mfma_f32_16x16x32_bf16 v[40:43], v[136:139], v[176:179], v[40:43]
	v_mfma_f32_16x16x32_bf16 v[28:31], v[128:131], v[184:187], v[28:31]
	v_mfma_f32_16x16x32_bf16 v[24:27], v[136:139], v[184:187], v[24:27]
	v_mfma_f32_16x16x32_bf16 v[12:15], v[128:131], v[192:195], v[12:15]
	v_mfma_f32_16x16x32_bf16 v[8:11], v[136:139], v[192:195], v[8:11]
	v_mfma_f32_16x16x32_bf16 v[60:63], v[132:135], v[172:175], v[60:63]
	v_mfma_f32_16x16x32_bf16 v[56:59], v[140:143], v[172:175], v[56:59]
	v_mfma_f32_16x16x32_bf16 v[44:47], v[132:135], v[180:183], v[44:47]
	v_mfma_f32_16x16x32_bf16 v[40:43], v[140:143], v[180:183], v[40:43]
	v_mfma_f32_16x16x32_bf16 v[28:31], v[132:135], v[188:191], v[28:31]
	v_mfma_f32_16x16x32_bf16 v[24:27], v[140:143], v[188:191], v[24:27]
	v_mfma_f32_16x16x32_bf16 v[12:15], v[132:135], v[196:199], v[12:15]
	v_mfma_f32_16x16x32_bf16 v[8:11], v[140:143], v[196:199], v[8:11]
	s_setprio 0
	s_barrier
	s_add_u32 s70, s4, 0x40000
	s_addc_u32 s71, s5, 0
	s_mov_b32 m0, s46
	v_lshl_add_u64 v[128:129], s[70:71], 0, v[144:145]
	global_load_lds_dwordx4 v[128:129], off
	v_lshl_add_u64 v[128:129], s[70:71], 0, v[146:147]
	s_mov_b32 m0, s47
	s_nop 0
	global_load_lds_dwordx4 v[128:129], off
	s_waitcnt vmcnt(6)
	s_barrier
	s_setprio 1
	v_mfma_f32_16x16x32_bf16 v[52:55], v[222:225], v[168:171], v[52:55]
	v_mfma_f32_16x16x32_bf16 v[48:51], v[230:233], v[168:171], v[48:51]
	v_mfma_f32_16x16x32_bf16 v[36:39], v[222:225], v[176:179], v[36:39]
	v_mfma_f32_16x16x32_bf16 v[32:35], v[230:233], v[176:179], v[32:35]
	v_mfma_f32_16x16x32_bf16 v[20:23], v[222:225], v[184:187], v[20:23]
	v_mfma_f32_16x16x32_bf16 v[16:19], v[230:233], v[184:187], v[16:19]
	v_mfma_f32_16x16x32_bf16 v[4:7], v[222:225], v[192:195], v[4:7]
	v_mfma_f32_16x16x32_bf16 v[0:3], v[230:233], v[192:195], v[0:3]
	v_mfma_f32_16x16x32_bf16 v[52:55], v[226:229], v[172:175], v[52:55]
	v_mfma_f32_16x16x32_bf16 v[48:51], v[234:237], v[172:175], v[48:51]
	v_mfma_f32_16x16x32_bf16 v[36:39], v[226:229], v[180:183], v[36:39]
	v_mfma_f32_16x16x32_bf16 v[32:35], v[234:237], v[180:183], v[32:35]
	v_mfma_f32_16x16x32_bf16 v[20:23], v[226:229], v[188:191], v[20:23]
	v_mfma_f32_16x16x32_bf16 v[16:19], v[234:237], v[188:191], v[16:19]
	v_mfma_f32_16x16x32_bf16 v[4:7], v[226:229], v[196:199], v[4:7]
	v_mfma_f32_16x16x32_bf16 v[0:3], v[234:237], v[196:199], v[0:3]
	s_setprio 0
	s_barrier
	ds_read_b128 v[128:131], v214
	ds_read_b128 v[132:135], v214 offset:1024
	ds_read_b128 v[136:139], v214 offset:2048
	ds_read_b128 v[140:143], v214 offset:3072
	s_add_u32 s6, s6, 0x40000
	s_addc_u32 s7, s7, 0
	s_mov_b32 m0, s48
	v_lshl_add_u64 v[222:223], s[6:7], 0, v[144:145]
	ds_read_b128 v[168:171], v212 offset:32768
	ds_read_b128 v[172:175], v212 offset:33792
	ds_read_b128 v[176:179], v212 offset:34816
	ds_read_b128 v[180:183], v212 offset:35840
	ds_read_b128 v[184:187], v212 offset:36864
	ds_read_b128 v[188:191], v212 offset:37888
	ds_read_b128 v[192:195], v212 offset:38912
	ds_read_b128 v[196:199], v212 offset:39936
	global_load_lds_dwordx4 v[222:223], off
	v_lshl_add_u64 v[222:223], s[6:7], 0, v[146:147]
	s_mov_b32 m0, s49
	s_nop 0
	global_load_lds_dwordx4 v[222:223], off
	s_waitcnt lgkmcnt(8)
	s_barrier
	s_waitcnt lgkmcnt(0)
	s_setprio 1
	s_waitcnt lgkmcnt(0)
	v_mfma_f32_16x16x32_bf16 v[124:127], v[128:131], v[168:171], v[124:127]
	v_mfma_f32_16x16x32_bf16 v[120:123], v[136:139], v[168:171], v[120:123]
	v_mfma_f32_16x16x32_bf16 v[108:111], v[128:131], v[176:179], v[108:111]
	v_mfma_f32_16x16x32_bf16 v[104:107], v[136:139], v[176:179], v[104:107]
	v_mfma_f32_16x16x32_bf16 v[92:95], v[128:131], v[184:187], v[92:95]
	v_mfma_f32_16x16x32_bf16 v[88:91], v[136:139], v[184:187], v[88:91]
	v_mfma_f32_16x16x32_bf16 v[76:79], v[128:131], v[192:195], v[76:79]
	v_mfma_f32_16x16x32_bf16 v[72:75], v[136:139], v[192:195], v[72:75]
	v_mfma_f32_16x16x32_bf16 v[124:127], v[132:135], v[172:175], v[124:127]
	v_mfma_f32_16x16x32_bf16 v[120:123], v[140:143], v[172:175], v[120:123]
	v_mfma_f32_16x16x32_bf16 v[108:111], v[132:135], v[180:183], v[108:111]
	v_mfma_f32_16x16x32_bf16 v[104:107], v[140:143], v[180:183], v[104:107]
	v_mfma_f32_16x16x32_bf16 v[92:95], v[132:135], v[188:191], v[92:95]
	v_mfma_f32_16x16x32_bf16 v[88:91], v[140:143], v[188:191], v[88:91]
	v_mfma_f32_16x16x32_bf16 v[76:79], v[132:135], v[196:199], v[76:79]
	v_mfma_f32_16x16x32_bf16 v[72:75], v[140:143], v[196:199], v[72:75]
	s_setprio 0
	s_barrier
	s_mov_b32 m0, s51
	v_lshl_add_u64 v[200:201], v[200:201], 0, s[18:19]
	ds_read_b128 v[222:225], v215
	ds_read_b128 v[226:229], v215 offset:1024
	ds_read_b128 v[230:233], v215 offset:2048
	ds_read_b128 v[234:237], v215 offset:3072
	global_load_lds_dwordx4 v[200:201], off
	v_lshl_add_u64 v[200:201], v[238:239], 0, s[18:19]
	s_mov_b32 m0, s52
	s_nop 0
	global_load_lds_dwordx4 v[200:201], off
	s_barrier
	s_waitcnt lgkmcnt(0)
	s_setprio 1
	s_waitcnt lgkmcnt(0)
	v_mfma_f32_16x16x32_bf16 v[116:119], v[222:225], v[168:171], v[116:119]
	v_mfma_f32_16x16x32_bf16 v[112:115], v[230:233], v[168:171], v[112:115]
	v_mfma_f32_16x16x32_bf16 v[100:103], v[222:225], v[176:179], v[100:103]
	v_mfma_f32_16x16x32_bf16 v[96:99], v[230:233], v[176:179], v[96:99]
	v_mfma_f32_16x16x32_bf16 v[84:87], v[222:225], v[184:187], v[84:87]
	v_mfma_f32_16x16x32_bf16 v[80:83], v[230:233], v[184:187], v[80:83]
	v_mfma_f32_16x16x32_bf16 v[68:71], v[222:225], v[192:195], v[68:71]
	v_mfma_f32_16x16x32_bf16 v[64:67], v[230:233], v[192:195], v[64:67]
	v_mfma_f32_16x16x32_bf16 v[116:119], v[226:229], v[172:175], v[116:119]
	v_mfma_f32_16x16x32_bf16 v[112:115], v[234:237], v[172:175], v[112:115]
	v_mfma_f32_16x16x32_bf16 v[100:103], v[226:229], v[180:183], v[100:103]
	v_mfma_f32_16x16x32_bf16 v[96:99], v[234:237], v[180:183], v[96:99]
	v_mfma_f32_16x16x32_bf16 v[84:87], v[226:229], v[188:191], v[84:87]
	v_mfma_f32_16x16x32_bf16 v[80:83], v[234:237], v[188:191], v[80:83]
	v_mfma_f32_16x16x32_bf16 v[68:71], v[226:229], v[196:199], v[68:71]
	v_mfma_f32_16x16x32_bf16 v[64:67], v[234:237], v[196:199], v[64:67]
	s_setprio 0
	s_mov_b32 m0, s54
	v_lshl_add_u64 v[200:201], v[240:241], 0, s[18:19]
	s_barrier
	ds_read_b128 v[168:171], v212 offset:49152
	ds_read_b128 v[172:175], v212 offset:50176
	ds_read_b128 v[176:179], v212 offset:51200
	ds_read_b128 v[180:183], v212 offset:52224
	ds_read_b128 v[184:187], v212 offset:53248
	ds_read_b128 v[188:191], v212 offset:54272
	ds_read_b128 v[192:195], v212 offset:55296
	ds_read_b128 v[196:199], v212 offset:56320
	global_load_lds_dwordx4 v[200:201], off
	v_lshl_add_u64 v[200:201], v[242:243], 0, s[18:19]
	s_mov_b32 m0, s55
	s_nop 0
	global_load_lds_dwordx4 v[200:201], off
	s_barrier
	s_waitcnt lgkmcnt(0)
	s_setprio 1
	s_waitcnt lgkmcnt(0)
	v_mfma_f32_16x16x32_bf16 v[60:63], v[128:131], v[168:171], v[60:63]
	v_mfma_f32_16x16x32_bf16 v[56:59], v[136:139], v[168:171], v[56:59]
	v_mfma_f32_16x16x32_bf16 v[44:47], v[128:131], v[176:179], v[44:47]
	v_mfma_f32_16x16x32_bf16 v[40:43], v[136:139], v[176:179], v[40:43]
	v_mfma_f32_16x16x32_bf16 v[28:31], v[128:131], v[184:187], v[28:31]
	v_mfma_f32_16x16x32_bf16 v[24:27], v[136:139], v[184:187], v[24:27]
	v_mfma_f32_16x16x32_bf16 v[12:15], v[128:131], v[192:195], v[12:15]
	v_mfma_f32_16x16x32_bf16 v[8:11], v[136:139], v[192:195], v[8:11]
	v_mfma_f32_16x16x32_bf16 v[60:63], v[132:135], v[172:175], v[60:63]
	v_mfma_f32_16x16x32_bf16 v[56:59], v[140:143], v[172:175], v[56:59]
	v_mfma_f32_16x16x32_bf16 v[44:47], v[132:135], v[180:183], v[44:47]
	v_mfma_f32_16x16x32_bf16 v[40:43], v[140:143], v[180:183], v[40:43]
	v_mfma_f32_16x16x32_bf16 v[28:31], v[132:135], v[188:191], v[28:31]
	v_mfma_f32_16x16x32_bf16 v[24:27], v[140:143], v[188:191], v[24:27]
	v_mfma_f32_16x16x32_bf16 v[12:15], v[132:135], v[196:199], v[12:15]
	v_mfma_f32_16x16x32_bf16 v[8:11], v[140:143], v[196:199], v[8:11]
	s_setprio 0
	s_barrier
	s_add_u32 s4, s4, 0x40080
	s_addc_u32 s5, s5, 0
	s_mov_b32 m0, s56
	v_lshl_add_u64 v[128:129], s[4:5], 0, v[144:145]
	global_load_lds_dwordx4 v[128:129], off
	v_lshl_add_u64 v[128:129], s[4:5], 0, v[146:147]
	s_mov_b32 m0, s57
	s_nop 0
	global_load_lds_dwordx4 v[128:129], off
	s_waitcnt vmcnt(6)
	s_barrier
	s_setprio 1
	v_mfma_f32_16x16x32_bf16 v[52:55], v[222:225], v[168:171], v[52:55]
	v_mfma_f32_16x16x32_bf16 v[48:51], v[230:233], v[168:171], v[48:51]
	v_mfma_f32_16x16x32_bf16 v[36:39], v[222:225], v[176:179], v[36:39]
	v_mfma_f32_16x16x32_bf16 v[32:35], v[230:233], v[176:179], v[32:35]
	v_mfma_f32_16x16x32_bf16 v[20:23], v[222:225], v[184:187], v[20:23]
	v_mfma_f32_16x16x32_bf16 v[16:19], v[230:233], v[184:187], v[16:19]
	v_mfma_f32_16x16x32_bf16 v[4:7], v[222:225], v[192:195], v[4:7]
	v_mfma_f32_16x16x32_bf16 v[0:3], v[230:233], v[192:195], v[0:3]
	v_mfma_f32_16x16x32_bf16 v[52:55], v[226:229], v[172:175], v[52:55]
	v_mfma_f32_16x16x32_bf16 v[48:51], v[234:237], v[172:175], v[48:51]
	v_mfma_f32_16x16x32_bf16 v[36:39], v[226:229], v[180:183], v[36:39]
	v_mfma_f32_16x16x32_bf16 v[32:35], v[234:237], v[180:183], v[32:35]
	v_mfma_f32_16x16x32_bf16 v[20:23], v[226:229], v[188:191], v[20:23]
	v_mfma_f32_16x16x32_bf16 v[16:19], v[234:237], v[188:191], v[16:19]
	v_mfma_f32_16x16x32_bf16 v[4:7], v[226:229], v[196:199], v[4:7]
	v_mfma_f32_16x16x32_bf16 v[0:3], v[234:237], v[196:199], v[0:3]
	s_setprio 0
	s_add_i32 s69, s69, 2
	s_add_u32 s2, s2, 0x100
	s_addc_u32 s3, s3, 0
	s_add_u32 s38, s38, 0x100
	s_addc_u32 s39, s39, 0
	s_cmp_gt_u32 s69, 13
	s_barrier
	s_cbranch_scc0 .LBB0_274
	s_lshl_b32 s11, s67, 8
	s_cmp_eq_u32 s68, 0
	s_mov_b32 s2, 0x6200000
	s_cselect_b32 s2, s2, 0x6221000
	s_add_u32 s2, s22, s2
	v_add_u32_e32 v176, s11, v204
	s_addc_u32 s3, s23, 0
	v_ashrrev_i32_e32 v177, 31, v176
	v_add_u32_e32 v198, s11, v205
	v_add_u32_e32 v196, s11, v206
	v_add_u32_e32 v194, s11, v207
	v_add_u32_e32 v192, 0x80, v176
	v_add_u32_e32 v190, 0x90, v176
	v_add_u32_e32 v188, 0xa0, v176
	v_add_u32_e32 v186, 0xb0, v176
	v_lshl_add_u64 v[128:129], v[176:177], 2, s[2:3]
	v_ashrrev_i32_e32 v199, 31, v198
	v_ashrrev_i32_e32 v197, 31, v196
	v_ashrrev_i32_e32 v195, 31, v194
	v_ashrrev_i32_e32 v193, 31, v192
	v_ashrrev_i32_e32 v191, 31, v190
	v_ashrrev_i32_e32 v189, 31, v188
	v_ashrrev_i32_e32 v187, 31, v186
	v_lshl_add_u64 v[130:131], v[198:199], 2, s[2:3]
	v_lshl_add_u64 v[132:133], v[196:197], 2, s[2:3]
	v_lshl_add_u64 v[134:135], v[194:195], 2, s[2:3]
	v_lshl_add_u64 v[136:137], v[192:193], 2, s[2:3]
	v_lshl_add_u64 v[138:139], v[190:191], 2, s[2:3]
	v_lshl_add_u64 v[140:141], v[188:189], 2, s[2:3]
	v_lshl_add_u64 v[142:143], v[186:187], 2, s[2:3]
	global_load_dword v184, v[128:129], off
	global_load_dword v182, v[130:131], off
	global_load_dword v180, v[132:133], off
	global_load_dword v178, v[134:135], off
	global_load_dword v174, v[136:137], off
	global_load_dword v172, v[138:139], off
	global_load_dword v170, v[140:141], off
	global_load_dword v168, v[142:143], off
	s_cmp_lt_i32 s33, 2
	s_cselect_b64 s[38:39], -1, 0
	s_cmp_gt_i32 s33, 1
	s_cselect_b64 s[2:3], -1, 0
	v_cndmask_b32_e64 v128, 0, 1, s[2:3]
	s_cmp_lg_u32 s68, 0
	s_mov_b64 s[6:7], -1
	v_cmp_ne_u32_e64 s[4:5], 1, v128
	s_cbranch_scc0 .LBB0_293
	s_lshl_b32 s6, s33, 8
	s_and_b32 s6, s6, 0x100
	v_or_b32_e32 v169, s6, v210
	s_and_b64 s[6:7], s[38:39], exec
	s_mov_b32 s6, 0x8600000
	s_cselect_b32 s6, s6, 0x8a00000
	s_add_u32 s6, s20, s6
	v_lshlrev_b32_e32 v148, 1, v169
	s_addc_u32 s7, s21, 0
	v_lshlrev_b64 v[222:223], 11, v[176:177]
	v_lshl_add_u64 v[200:201], s[26:27], 0, v[148:149]
	v_lshl_add_u64 v[222:223], s[6:7], 0, v[222:223]
	v_lshlrev_b32_e32 v148, 2, v169
	s_waitcnt vmcnt(0)
	v_pk_mul_f32 v[130:131], v[126:127], v[184:185] op_sel_hi:[1,0]
	v_pk_mul_f32 v[128:129], v[124:125], v[184:185] op_sel_hi:[1,0]
	v_pk_mul_f32 v[134:135], v[122:123], v[184:185] op_sel_hi:[1,0]
	v_pk_mul_f32 v[132:133], v[120:121], v[184:185] op_sel_hi:[1,0]
	v_pk_mul_f32 v[138:139], v[118:119], v[184:185] op_sel_hi:[1,0]
	v_pk_mul_f32 v[136:137], v[116:117], v[184:185] op_sel_hi:[1,0]
	v_pk_mul_f32 v[142:143], v[114:115], v[184:185] op_sel_hi:[1,0]
	v_pk_mul_f32 v[140:141], v[112:113], v[184:185] op_sel_hi:[1,0]
	v_lshl_add_u64 v[222:223], v[222:223], 0, v[148:149]
	s_and_b64 vcc, exec, s[4:5]
	global_store_dwordx4 v[222:223], v[128:131], off
	global_store_dwordx4 v[222:223], v[132:135], off offset:16
	global_store_dwordx4 v[222:223], v[136:139], off offset:128
	global_store_dwordx4 v[222:223], v[140:143], off offset:144
	s_cbranch_vccnz .LBB0_278
	v_lshlrev_b64 v[222:223], 9, v[176:177]
	v_lshl_add_u64 v[222:223], v[222:223], 1, v[200:201]
	v_cvt_pk_bf16_f32 v128, v128, v129
	v_cvt_pk_bf16_f32 v129, v130, v131
	v_cvt_pk_bf16_f32 v130, v132, v133
	v_cvt_pk_bf16_f32 v131, v134, v135
	global_store_dwordx4 v[222:223], v[128:131], off nt
	s_nop 1
	v_cvt_pk_bf16_f32 v128, v136, v137
	v_cvt_pk_bf16_f32 v129, v138, v139
	v_cvt_pk_bf16_f32 v130, v140, v141
	v_cvt_pk_bf16_f32 v131, v142, v143
	global_store_dwordx4 v[222:223], v[128:131], off offset:64 nt
